# pre-flush by the arriver that leaves a quarter of the XCC outstanding (instead of half)
# baseline (speedup 1.0000x reference)
.Lgb_half_s0:
	s_lshr_b32 s7, s98, 2
	s_sub_u32 s7, s6, s7
	v_cmp_eq_u32_e32 vcc, s7, v1
	s_cbranch_vccz .Lgb_inv_s0
	buffer_wbl2 sc1
